# QK^T K-fragment ds_reads software-pipelined 3 steps ahead in both attention loops
# speedup vs baseline: 1.0020x; 1.0020x over previous
.LBB0_717:
	s_sub_i32 s6, s53, 63
	s_cmp_le_u32 s6, s59
	s_cselect_b64 s[18:19], -1, 0
	s_cmp_gt_u32 s6, s59
	s_mul_i32 s62, s54, 0xa000
	s_cbranch_scc1 .LBB0_719
	v_add_u32_e32 v1, s62, v195
	v_add_u32_e32 v13, s62, v204
	v_add_u32_e32 v14, v1, v196
	ds_read_b128 v[2:5], v14
	ds_read_b128 v[6:9], v14 offset:8192
	v_add_u32_e32 v15, v1, v197
	ds_read_b128 v[220:223], v15
	ds_read_b128 v[224:227], v15 offset:8192
	v_add_u32_e32 v14, v1, v198
	ds_read_b128 v[228:231], v14
	ds_read_b128 v[232:235], v14 offset:8192
	s_waitcnt lgkmcnt(4)
	v_mfma_f32_32x32x16_bf16 v[16:31], v[2:5], v[112:115], 0
	v_mfma_f32_32x32x16_bf16 v[32:47], v[6:9], v[112:115], 0
	v_add_u32_e32 v15, v1, v199
	ds_read_b128 v[236:239], v15
	ds_read_b128 v[240:243], v15 offset:8192
	s_waitcnt lgkmcnt(4)
	v_mfma_f32_32x32x16_bf16 v[16:31], v[220:223], v[116:119], v[16:31]
	v_mfma_f32_32x32x16_bf16 v[32:47], v[224:227], v[116:119], v[32:47]
	v_add_u32_e32 v14, v1, v200
	ds_read_b128 v[2:5], v14
	ds_read_b128 v[6:9], v14 offset:8192
	s_waitcnt lgkmcnt(4)
	v_mfma_f32_32x32x16_bf16 v[16:31], v[228:231], v[120:123], v[16:31]
	v_mfma_f32_32x32x16_bf16 v[32:47], v[232:235], v[120:123], v[32:47]
	v_add_u32_e32 v15, v1, v201
	ds_read_b128 v[220:223], v15
	ds_read_b128 v[224:227], v15 offset:8192
	s_waitcnt lgkmcnt(4)
	v_mfma_f32_32x32x16_bf16 v[16:31], v[236:239], v[124:127], v[16:31]
	v_mfma_f32_32x32x16_bf16 v[32:47], v[240:243], v[124:127], v[32:47]
	v_add_u32_e32 v14, v1, v202
	ds_read_b128 v[228:231], v14
	ds_read_b128 v[232:235], v14 offset:8192
	s_waitcnt lgkmcnt(4)
	v_mfma_f32_32x32x16_bf16 v[16:31], v[2:5], v[128:131], v[16:31]
	v_mfma_f32_32x32x16_bf16 v[32:47], v[6:9], v[128:131], v[32:47]
	v_add_u32_e32 v15, v1, v203
	ds_read_b128 v[236:239], v15
	ds_read_b128 v[240:243], v15 offset:8192
	s_waitcnt lgkmcnt(4)
	v_mfma_f32_32x32x16_bf16 v[16:31], v[220:223], v[132:135], v[16:31]
	v_mfma_f32_32x32x16_bf16 v[32:47], v[224:227], v[132:135], v[32:47]
	v_add_u32_e32 v14, v13, v205
	ds_read_b128 v[2:5], v14 offset:16384
	ds_read_b128 v[6:9], v14 offset:20480
	s_waitcnt lgkmcnt(4)
	v_mfma_f32_32x32x16_bf16 v[16:31], v[228:231], v[136:139], v[16:31]
	v_mfma_f32_32x32x16_bf16 v[32:47], v[232:235], v[136:139], v[32:47]
	v_add_u32_e32 v15, v13, v206
	ds_read_b128 v[220:223], v15 offset:16384
	ds_read_b128 v[224:227], v15 offset:20480
	s_waitcnt lgkmcnt(4)
	v_mfma_f32_32x32x16_bf16 v[16:31], v[236:239], v[140:143], v[16:31]
	v_mfma_f32_32x32x16_bf16 v[32:47], v[240:243], v[140:143], v[32:47]
	v_add_u32_e32 v14, v13, v207
	ds_read_b128 v[228:231], v14 offset:16384
	ds_read_b128 v[232:235], v14 offset:20480
	s_waitcnt lgkmcnt(4)
	v_mfma_f32_32x32x16_bf16 v[16:31], v[2:5], v[144:147], v[16:31]
	v_mfma_f32_32x32x16_bf16 v[32:47], v[6:9], v[144:147], v[32:47]
	v_add_u32_e32 v15, v13, v208
	ds_read_b128 v[236:239], v15 offset:16384
	ds_read_b128 v[240:243], v15 offset:20480
	s_waitcnt lgkmcnt(4)
	v_mfma_f32_32x32x16_bf16 v[16:31], v[220:223], v[148:151], v[16:31]
	v_mfma_f32_32x32x16_bf16 v[32:47], v[224:227], v[148:151], v[32:47]
	s_waitcnt lgkmcnt(2)
	v_mfma_f32_32x32x16_bf16 v[16:31], v[228:231], v[152:155], v[16:31]
	v_mfma_f32_32x32x16_bf16 v[32:47], v[232:235], v[152:155], v[32:47]
	s_waitcnt lgkmcnt(0)
	v_mfma_f32_32x32x16_bf16 v[16:31], v[236:239], v[156:159], v[16:31]
	v_mfma_f32_32x32x16_bf16 v[32:47], v[240:243], v[156:159], v[32:47]

.LBB0_1511:
	s_sub_i32 s26, s83, 63
	s_cmp_le_u32 s26, s86
	s_cselect_b64 s[38:39], -1, 0
	s_cmp_gt_u32 s26, s86
	s_cbranch_scc1 .LBB0_1513
	v_lshl_add_u32 v1, s80, 15, v178
	ds_read_b128 v[16:19], v203
	ds_read_b128 v[20:23], v203 offset:32
	ds_read_b128 v[24:27], v203 offset:64
	ds_read_b128 v[28:31], v203 offset:96
	ds_read_b128 v[32:35], v203 offset:128
	ds_read_b128 v[36:39], v203 offset:160
	ds_read_b128 v[40:43], v203 offset:192
	ds_read_b128 v[44:47], v203 offset:224
	v_add_u32_e32 v14, v1, v179
	ds_read_b128 v[2:5], v14
	ds_read_b128 v[6:9], v14 offset:8192
	v_add_u32_e32 v15, v1, v180
	ds_read_b128 v[208:211], v15
	ds_read_b128 v[212:215], v15 offset:8192
	v_add_u32_e32 v14, v1, v181
	ds_read_b128 v[216:219], v14
	ds_read_b128 v[220:223], v14 offset:8192
	s_waitcnt lgkmcnt(4)
	v_mfma_f32_32x32x16_bf16 v[16:31], v[2:5], v[112:115], v[16:31]
	v_mfma_f32_32x32x16_bf16 v[32:47], v[6:9], v[112:115], v[32:47]
	v_add_u32_e32 v15, v1, v182
	ds_read_b128 v[224:227], v15
	ds_read_b128 v[228:231], v15 offset:8192
	s_waitcnt lgkmcnt(4)
	v_mfma_f32_32x32x16_bf16 v[16:31], v[208:211], v[116:119], v[16:31]
	v_mfma_f32_32x32x16_bf16 v[32:47], v[212:215], v[116:119], v[32:47]
	v_add_u32_e32 v14, v1, v183
	ds_read_b128 v[2:5], v14
	ds_read_b128 v[6:9], v14 offset:8192
	s_waitcnt lgkmcnt(4)
	v_mfma_f32_32x32x16_bf16 v[16:31], v[216:219], v[120:123], v[16:31]
	v_mfma_f32_32x32x16_bf16 v[32:47], v[220:223], v[120:123], v[32:47]
	v_add_u32_e32 v15, v1, v184
	ds_read_b128 v[208:211], v15
	ds_read_b128 v[212:215], v15 offset:8192
	s_waitcnt lgkmcnt(4)
	v_mfma_f32_32x32x16_bf16 v[16:31], v[224:227], v[124:127], v[16:31]
	v_mfma_f32_32x32x16_bf16 v[32:47], v[228:231], v[124:127], v[32:47]
	v_add_u32_e32 v14, v1, v185
	ds_read_b128 v[216:219], v14
	ds_read_b128 v[220:223], v14 offset:8192
	s_waitcnt lgkmcnt(4)
	v_mfma_f32_32x32x16_bf16 v[16:31], v[2:5], v[128:131], v[16:31]
	v_mfma_f32_32x32x16_bf16 v[32:47], v[6:9], v[128:131], v[32:47]
	v_add_u32_e32 v15, v1, v186
	ds_read_b128 v[224:227], v15
	ds_read_b128 v[228:231], v15 offset:8192
	s_waitcnt lgkmcnt(4)
	v_mfma_f32_32x32x16_bf16 v[16:31], v[208:211], v[132:135], v[16:31]
	v_mfma_f32_32x32x16_bf16 v[32:47], v[212:215], v[132:135], v[32:47]
	s_waitcnt lgkmcnt(2)
	v_mfma_f32_32x32x16_bf16 v[16:31], v[216:219], v[136:139], v[16:31]
	v_mfma_f32_32x32x16_bf16 v[32:47], v[220:223], v[136:139], v[32:47]
	s_waitcnt lgkmcnt(0)
	v_mfma_f32_32x32x16_bf16 v[16:31], v[224:227], v[140:143], v[16:31]
	v_mfma_f32_32x32x16_bf16 v[32:47], v[228:231], v[140:143], v[32:47]
